# G4 epilogue: bf16 tile stores in the quad-contiguous lane layout (row / column lane parts replaced at the root, 4 ds_bpermute per 16-byte store)
# baseline (speedup 1.0000x reference)
.LBB0_1243:
	v_and_b32_e32 v238, -16, v146
	v_lshrrev_b32_e32 v239, 2, v186
	v_and_b32_e32 v241, 3, v186
	v_add_u32_e32 v238, v238, v239
	v_lshl_add_u32 v142, s8, 8, v238
	v_and_b32_e32 v240, -25, v148
	v_lshl_or_b32 v240, v241, 3, v240
	v_lshl_add_u32 v241, v241, 4, v239
	v_lshlrev_b32_e32 v241, 2, v241
	v_and_b32_e32 v140, -16, v142
	v_lshlrev_b32_e32 v140, 6, v140
	v_lshl_add_u32 v140, v186, 4, v140
	v_add_u32_e32 v230, 0x2000, v140
	global_load_dwordx4 v[198:201], v140, s[2:3]
	global_load_dwordx4 v[202:205], v140, s[2:3] offset:1024
	global_load_dwordx4 v[206:209], v140, s[2:3] offset:2048
	global_load_dwordx4 v[210:213], v140, s[2:3] offset:3072
	global_load_dwordx4 v[214:217], v230, s[2:3]
	global_load_dwordx4 v[218:221], v230, s[2:3] offset:1024
	global_load_dwordx4 v[222:225], v230, s[2:3] offset:2048
	global_load_dwordx4 v[226:229], v230, s[2:3] offset:3072
	v_and_b32_e32 v231, 15, v186
	v_lshlrev_b32_e32 v231, 4, v231
	s_waitcnt vmcnt(0)
	v_add_f32_e32 v198, v198, v199
	v_add_f32_e32 v200, v200, v201
	v_add_f32_e32 v202, v202, v203
	v_add_f32_e32 v204, v204, v205
	v_add_f32_e32 v206, v206, v207
	v_add_f32_e32 v208, v208, v209
	v_add_f32_e32 v210, v210, v211
	v_add_f32_e32 v212, v212, v213
	v_add_f32_e32 v214, v214, v215
	v_add_f32_e32 v216, v216, v217
	v_add_f32_e32 v218, v218, v219
	v_add_f32_e32 v220, v220, v221
	v_add_f32_e32 v222, v222, v223
	v_add_f32_e32 v224, v224, v225
	v_add_f32_e32 v226, v226, v227
	v_add_f32_e32 v228, v228, v229
	v_add_f32_e32 v198, v198, v200
	v_add_f32_e32 v202, v202, v204
	v_add_f32_e32 v206, v206, v208
	v_add_f32_e32 v210, v210, v212
	v_add_f32_e32 v214, v214, v216
	v_add_f32_e32 v218, v218, v220
	v_add_f32_e32 v222, v222, v224
	v_add_f32_e32 v226, v226, v228
	v_add_f32_dpp v198, v198, v198 quad_perm:[1,0,3,2] row_mask:0xf bank_mask:0xf
	v_add_f32_dpp v202, v202, v202 quad_perm:[1,0,3,2] row_mask:0xf bank_mask:0xf
	v_add_f32_dpp v206, v206, v206 quad_perm:[1,0,3,2] row_mask:0xf bank_mask:0xf
	v_add_f32_dpp v210, v210, v210 quad_perm:[1,0,3,2] row_mask:0xf bank_mask:0xf
	v_add_f32_dpp v214, v214, v214 quad_perm:[1,0,3,2] row_mask:0xf bank_mask:0xf
	v_add_f32_dpp v218, v218, v218 quad_perm:[1,0,3,2] row_mask:0xf bank_mask:0xf
	v_add_f32_dpp v222, v222, v222 quad_perm:[1,0,3,2] row_mask:0xf bank_mask:0xf
	v_add_f32_dpp v226, v226, v226 quad_perm:[1,0,3,2] row_mask:0xf bank_mask:0xf
	v_add_f32_dpp v198, v198, v198 quad_perm:[2,3,0,1] row_mask:0xf bank_mask:0xf
	v_add_f32_dpp v202, v202, v202 quad_perm:[2,3,0,1] row_mask:0xf bank_mask:0xf
	v_add_f32_dpp v206, v206, v206 quad_perm:[2,3,0,1] row_mask:0xf bank_mask:0xf
	v_add_f32_dpp v210, v210, v210 quad_perm:[2,3,0,1] row_mask:0xf bank_mask:0xf
	v_add_f32_dpp v214, v214, v214 quad_perm:[2,3,0,1] row_mask:0xf bank_mask:0xf
	v_add_f32_dpp v218, v218, v218 quad_perm:[2,3,0,1] row_mask:0xf bank_mask:0xf
	v_add_f32_dpp v222, v222, v222 quad_perm:[2,3,0,1] row_mask:0xf bank_mask:0xf
	v_add_f32_dpp v226, v226, v226 quad_perm:[2,3,0,1] row_mask:0xf bank_mask:0xf
	v_fmamk_f32 v198, v198, 0x3a800000, v182
	v_fmamk_f32 v202, v202, 0x3a800000, v182
	v_fmamk_f32 v206, v206, 0x3a800000, v182
	v_fmamk_f32 v210, v210, 0x3a800000, v182
	v_fmamk_f32 v214, v214, 0x3a800000, v182
	v_fmamk_f32 v218, v218, 0x3a800000, v182
	v_fmamk_f32 v222, v222, 0x3a800000, v182
	v_fmamk_f32 v226, v226, 0x3a800000, v182
	v_mul_f32_e32 v199, 0x4b800000, v198
	v_mul_f32_e32 v203, 0x4b800000, v202
	v_mul_f32_e32 v207, 0x4b800000, v206
	v_mul_f32_e32 v211, 0x4b800000, v210
	v_mul_f32_e32 v215, 0x4b800000, v214
	v_mul_f32_e32 v219, 0x4b800000, v218
	v_mul_f32_e32 v223, 0x4b800000, v222
	v_mul_f32_e32 v227, 0x4b800000, v226
	v_cmp_gt_f32_e32 vcc, 0x800000, v198
	s_nop 1
	v_cndmask_b32_e32 v200, v198, v199, vcc
	v_rsq_f32_e32 v200, v200
	s_nop 0
	v_mul_f32_e32 v201, 0x45800000, v200
	v_cndmask_b32_e32 v200, v200, v201, vcc
	v_cmp_gt_f32_e32 vcc, 0x800000, v202
	s_nop 1
	v_cndmask_b32_e32 v204, v202, v203, vcc
	v_rsq_f32_e32 v204, v204
	s_nop 0
	v_mul_f32_e32 v205, 0x45800000, v204
	v_cndmask_b32_e32 v204, v204, v205, vcc
	v_cmp_gt_f32_e32 vcc, 0x800000, v206
	s_nop 1
	v_cndmask_b32_e32 v208, v206, v207, vcc
	v_rsq_f32_e32 v208, v208
	s_nop 0
	v_mul_f32_e32 v209, 0x45800000, v208
	v_cndmask_b32_e32 v208, v208, v209, vcc
	v_cmp_gt_f32_e32 vcc, 0x800000, v210
	s_nop 1
	v_cndmask_b32_e32 v212, v210, v211, vcc
	v_rsq_f32_e32 v212, v212
	s_nop 0
	v_mul_f32_e32 v213, 0x45800000, v212
	v_cndmask_b32_e32 v212, v212, v213, vcc
	v_cmp_gt_f32_e32 vcc, 0x800000, v214
	s_nop 1
	v_cndmask_b32_e32 v216, v214, v215, vcc
	v_rsq_f32_e32 v216, v216
	s_nop 0
	v_mul_f32_e32 v217, 0x45800000, v216
	v_cndmask_b32_e32 v216, v216, v217, vcc
	v_cmp_gt_f32_e32 vcc, 0x800000, v218
	s_nop 1
	v_cndmask_b32_e32 v220, v218, v219, vcc
	v_rsq_f32_e32 v220, v220
	s_nop 0
	v_mul_f32_e32 v221, 0x45800000, v220
	v_cndmask_b32_e32 v220, v220, v221, vcc
	v_cmp_gt_f32_e32 vcc, 0x800000, v222
	s_nop 1
	v_cndmask_b32_e32 v224, v222, v223, vcc
	v_rsq_f32_e32 v224, v224
	s_nop 0
	v_mul_f32_e32 v225, 0x45800000, v224
	v_cndmask_b32_e32 v224, v224, v225, vcc
	v_cmp_gt_f32_e32 vcc, 0x800000, v226
	s_nop 1
	v_cndmask_b32_e32 v228, v226, v227, vcc
	v_rsq_f32_e32 v228, v228
	s_nop 0
	v_mul_f32_e32 v229, 0x45800000, v228
	v_cndmask_b32_e32 v228, v228, v229, vcc
	s_nop 1
	ds_bpermute_b32 v242, v231, v200
	ds_bpermute_b32 v243, v231, v204
	ds_bpermute_b32 v244, v231, v208
	ds_bpermute_b32 v245, v231, v212
	ds_bpermute_b32 v246, v231, v216
	ds_bpermute_b32 v247, v231, v220
	ds_bpermute_b32 v248, v231, v224
	ds_bpermute_b32 v249, v231, v228
	s_waitcnt lgkmcnt(0)
	v_ashrrev_i32_e32 v143, 31, v142
	v_lshlrev_b64 v[140:141], 6, v[142:143]
	v_lshl_add_u64 v[140:141], s[2:3], 0, v[140:141]
	v_lshl_or_b32 v140, s0, 8, v240
	s_movk_i32 s0, 0x1000
	v_mov_b32_e32 v144, v242
	v_mov_b32_e32 v145, v144
	v_cmp_gt_i32_e32 vcc, s0, v140
	s_and_saveexec_b64 s[0:1], vcc
	s_cbranch_execz .LBB0_1245
	v_mov_b32_e32 v150, v144
	v_mov_b32_e32 v151, v144
	v_pk_mul_f32 v[126:127], v[126:127], v[144:145]
	v_pk_mul_f32 v[122:123], v[122:123], v[144:145]
	v_pk_mul_f32 v[128:129], v[128:129], v[150:151]
	v_max_f32_e32 v126, 0, v126
	v_max_f32_e32 v122, 0, v122
	v_max_f32_e32 v127, 0, v127
	v_max_f32_e32 v123, 0, v123
	v_pk_mul_f32 v[124:125], v[124:125], v[150:151]
	v_pk_mul_f32 v[126:127], v[126:127], v[126:127]
	v_pk_mul_f32 v[150:151], v[122:123], v[122:123]
	v_max_f32_e32 v122, 0, v128
	v_max_f32_e32 v123, 0, v129
	v_max_f32_e32 v124, 0, v124
	v_max_f32_e32 v125, 0, v125
	v_pk_mul_f32 v[128:129], v[122:123], v[122:123]
	v_cvt_pk_bf16_f32 v122, v126, v127
	v_lshlrev_b64 v[126:127], 13, v[142:143]
	v_pk_mul_f32 v[152:153], v[124:125], v[124:125]
	v_lshl_add_u64 v[126:127], s[10:11], 0, v[126:127]
	v_ashrrev_i32_e32 v141, 31, v140
	v_cvt_pk_bf16_f32 v123, v128, v129
	v_cvt_pk_bf16_f32 v124, v150, v151
	v_cvt_pk_bf16_f32 v125, v152, v153
	v_lshl_add_u64 v[126:127], v[140:141], 1, v[126:127]
	ds_bpermute_b32 v122, v241, v122
	ds_bpermute_b32 v123, v241, v123
	ds_bpermute_b32 v124, v241, v124
	ds_bpermute_b32 v125, v241, v125
	s_waitcnt lgkmcnt(0)
	global_store_dwordx4 v[126:127], v[122:125], off
.LBB0_1245:
	s_or_b64 exec, exec, s[0:1]
	s_nop 0
	v_or_b32_e32 v122, 0x80, v140
	s_movk_i32 s0, 0x1000
	v_cmp_gt_i32_e64 s[8:9], s0, v122
	s_and_saveexec_b64 s[0:1], s[8:9]
	s_cbranch_execz .LBB0_1247
	v_mov_b32_e32 v122, v144
	v_mov_b32_e32 v123, v144
	v_pk_mul_f32 v[118:119], v[118:119], v[144:145]
	v_pk_mul_f32 v[114:115], v[114:115], v[144:145]
	v_pk_mul_f32 v[120:121], v[120:121], v[122:123]
	v_max_f32_e32 v118, 0, v118
	v_max_f32_e32 v114, 0, v114
	v_max_f32_e32 v119, 0, v119
	v_max_f32_e32 v115, 0, v115
	v_pk_mul_f32 v[116:117], v[116:117], v[122:123]
	v_pk_mul_f32 v[118:119], v[118:119], v[118:119]
	v_pk_mul_f32 v[122:123], v[114:115], v[114:115]
	v_max_f32_e32 v114, 0, v120
	v_max_f32_e32 v115, 0, v121
	v_max_f32_e32 v116, 0, v116
	v_max_f32_e32 v117, 0, v117
	v_pk_mul_f32 v[120:121], v[114:115], v[114:115]
	v_cvt_pk_bf16_f32 v114, v118, v119
	v_lshlrev_b64 v[118:119], 13, v[142:143]
	v_pk_mul_f32 v[124:125], v[116:117], v[116:117]
	v_lshl_add_u64 v[118:119], s[10:11], 0, v[118:119]
	v_ashrrev_i32_e32 v141, 31, v140
	v_cvt_pk_bf16_f32 v115, v120, v121
	v_cvt_pk_bf16_f32 v116, v122, v123
	v_cvt_pk_bf16_f32 v117, v124, v125
	v_lshl_add_u64 v[118:119], v[140:141], 1, v[118:119]
	ds_bpermute_b32 v114, v241, v114
	ds_bpermute_b32 v115, v241, v115
	ds_bpermute_b32 v116, v241, v116
	ds_bpermute_b32 v117, v241, v117
	s_waitcnt lgkmcnt(0)
	global_store_dwordx4 v[118:119], v[114:117], off offset:256
.LBB0_1247:
	s_or_b64 exec, exec, s[0:1]
	s_nop 0
	v_or_b32_e32 v114, 16, v142
	v_ashrrev_i32_e32 v115, 31, v114
	v_lshlrev_b64 v[116:117], 6, v[114:115]
	v_lshl_add_u64 v[128:129], s[2:3], 0, v[116:117]
	v_mov_b32_e32 v116, v243
	v_mov_b32_e32 v117, v116
	s_and_saveexec_b64 s[0:1], vcc
	s_cbranch_execz .LBB0_1249
	v_mov_b32_e32 v118, v116
	v_mov_b32_e32 v119, v116
	v_pk_mul_f32 v[110:111], v[110:111], v[116:117]
	v_pk_mul_f32 v[106:107], v[106:107], v[116:117]
	v_pk_mul_f32 v[112:113], v[112:113], v[118:119]
	v_max_f32_e32 v110, 0, v110
	v_max_f32_e32 v106, 0, v106
	v_max_f32_e32 v111, 0, v111
	v_max_f32_e32 v107, 0, v107
	v_pk_mul_f32 v[108:109], v[108:109], v[118:119]
	v_pk_mul_f32 v[110:111], v[110:111], v[110:111]
	v_pk_mul_f32 v[118:119], v[106:107], v[106:107]
	v_max_f32_e32 v106, 0, v112
	v_max_f32_e32 v107, 0, v113
	v_max_f32_e32 v108, 0, v108
	v_max_f32_e32 v109, 0, v109
	v_pk_mul_f32 v[112:113], v[106:107], v[106:107]
	v_cvt_pk_bf16_f32 v106, v110, v111
	v_lshlrev_b64 v[110:111], 13, v[114:115]
	v_pk_mul_f32 v[120:121], v[108:109], v[108:109]
	v_lshl_add_u64 v[110:111], s[10:11], 0, v[110:111]
	v_ashrrev_i32_e32 v141, 31, v140
	v_cvt_pk_bf16_f32 v107, v112, v113
	v_cvt_pk_bf16_f32 v108, v118, v119
	v_cvt_pk_bf16_f32 v109, v120, v121
	v_lshl_add_u64 v[110:111], v[140:141], 1, v[110:111]
	ds_bpermute_b32 v106, v241, v106
	ds_bpermute_b32 v107, v241, v107
	ds_bpermute_b32 v108, v241, v108
	ds_bpermute_b32 v109, v241, v109
	s_waitcnt lgkmcnt(0)
	global_store_dwordx4 v[110:111], v[106:109], off
.LBB0_1249:
	s_or_b64 exec, exec, s[0:1]
	s_and_saveexec_b64 s[0:1], s[8:9]
	s_cbranch_execz .LBB0_1251
	v_mov_b32_e32 v106, v116
	v_mov_b32_e32 v107, v116
	v_pk_mul_f32 v[102:103], v[102:103], v[116:117]
	v_pk_mul_f32 v[98:99], v[98:99], v[116:117]
	v_pk_mul_f32 v[104:105], v[104:105], v[106:107]
	v_max_f32_e32 v102, 0, v102
	v_max_f32_e32 v98, 0, v98
	v_max_f32_e32 v103, 0, v103
	v_max_f32_e32 v99, 0, v99
	v_pk_mul_f32 v[100:101], v[100:101], v[106:107]
	v_pk_mul_f32 v[102:103], v[102:103], v[102:103]
	v_pk_mul_f32 v[106:107], v[98:99], v[98:99]
	v_max_f32_e32 v98, 0, v104
	v_max_f32_e32 v99, 0, v105
	v_max_f32_e32 v100, 0, v100
	v_max_f32_e32 v101, 0, v101
	v_pk_mul_f32 v[104:105], v[98:99], v[98:99]
	v_cvt_pk_bf16_f32 v98, v102, v103
	v_lshlrev_b64 v[102:103], 13, v[114:115]
	v_pk_mul_f32 v[108:109], v[100:101], v[100:101]
	v_lshl_add_u64 v[102:103], s[10:11], 0, v[102:103]
	v_ashrrev_i32_e32 v141, 31, v140
	v_cvt_pk_bf16_f32 v99, v104, v105
	v_cvt_pk_bf16_f32 v100, v106, v107
	v_cvt_pk_bf16_f32 v101, v108, v109
	v_lshl_add_u64 v[102:103], v[140:141], 1, v[102:103]
	ds_bpermute_b32 v98, v241, v98
	ds_bpermute_b32 v99, v241, v99
	ds_bpermute_b32 v100, v241, v100
	ds_bpermute_b32 v101, v241, v101
	s_waitcnt lgkmcnt(0)
	global_store_dwordx4 v[102:103], v[98:101], off offset:256
.LBB0_1251:
	s_or_b64 exec, exec, s[0:1]
	s_nop 0
	v_or_b32_e32 v98, 32, v142
	v_ashrrev_i32_e32 v99, 31, v98
	v_lshlrev_b64 v[100:101], 6, v[98:99]
	v_lshl_add_u64 v[112:113], s[2:3], 0, v[100:101]
	v_mov_b32_e32 v100, v244
	v_mov_b32_e32 v101, v100
	s_and_saveexec_b64 s[0:1], vcc
	s_cbranch_execz .LBB0_1253
	v_mov_b32_e32 v102, v100
	v_mov_b32_e32 v103, v100
	v_pk_mul_f32 v[94:95], v[94:95], v[100:101]
	v_pk_mul_f32 v[90:91], v[90:91], v[100:101]
	v_pk_mul_f32 v[96:97], v[96:97], v[102:103]
	v_max_f32_e32 v94, 0, v94
	v_max_f32_e32 v90, 0, v90
	v_max_f32_e32 v95, 0, v95
	v_max_f32_e32 v91, 0, v91
	v_pk_mul_f32 v[92:93], v[92:93], v[102:103]
	v_pk_mul_f32 v[94:95], v[94:95], v[94:95]
	v_pk_mul_f32 v[102:103], v[90:91], v[90:91]
	v_max_f32_e32 v90, 0, v96
	v_max_f32_e32 v91, 0, v97
	v_max_f32_e32 v92, 0, v92
	v_max_f32_e32 v93, 0, v93
	v_pk_mul_f32 v[96:97], v[90:91], v[90:91]
	v_cvt_pk_bf16_f32 v90, v94, v95
	v_lshlrev_b64 v[94:95], 13, v[98:99]
	v_pk_mul_f32 v[104:105], v[92:93], v[92:93]
	v_lshl_add_u64 v[94:95], s[10:11], 0, v[94:95]
	v_ashrrev_i32_e32 v141, 31, v140
	v_cvt_pk_bf16_f32 v91, v96, v97
	v_cvt_pk_bf16_f32 v92, v102, v103
	v_cvt_pk_bf16_f32 v93, v104, v105
	v_lshl_add_u64 v[94:95], v[140:141], 1, v[94:95]
	ds_bpermute_b32 v90, v241, v90
	ds_bpermute_b32 v91, v241, v91
	ds_bpermute_b32 v92, v241, v92
	ds_bpermute_b32 v93, v241, v93
	s_waitcnt lgkmcnt(0)
	global_store_dwordx4 v[94:95], v[90:93], off
.LBB0_1253:
	s_or_b64 exec, exec, s[0:1]
	s_and_saveexec_b64 s[0:1], s[8:9]
	s_cbranch_execz .LBB0_1255
	v_mov_b32_e32 v90, v100
	v_mov_b32_e32 v91, v100
	v_pk_mul_f32 v[86:87], v[86:87], v[100:101]
	v_pk_mul_f32 v[82:83], v[82:83], v[100:101]
	v_pk_mul_f32 v[88:89], v[88:89], v[90:91]
	v_max_f32_e32 v86, 0, v86
	v_max_f32_e32 v82, 0, v82
	v_max_f32_e32 v87, 0, v87
	v_max_f32_e32 v83, 0, v83
	v_pk_mul_f32 v[84:85], v[84:85], v[90:91]
	v_pk_mul_f32 v[86:87], v[86:87], v[86:87]
	v_pk_mul_f32 v[90:91], v[82:83], v[82:83]
	v_max_f32_e32 v82, 0, v88
	v_max_f32_e32 v83, 0, v89
	v_max_f32_e32 v84, 0, v84
	v_max_f32_e32 v85, 0, v85
	v_pk_mul_f32 v[88:89], v[82:83], v[82:83]
	v_cvt_pk_bf16_f32 v82, v86, v87
	v_lshlrev_b64 v[86:87], 13, v[98:99]
	v_pk_mul_f32 v[92:93], v[84:85], v[84:85]
	v_lshl_add_u64 v[86:87], s[10:11], 0, v[86:87]
	v_ashrrev_i32_e32 v141, 31, v140
	v_cvt_pk_bf16_f32 v83, v88, v89
	v_cvt_pk_bf16_f32 v84, v90, v91
	v_cvt_pk_bf16_f32 v85, v92, v93
	v_lshl_add_u64 v[86:87], v[140:141], 1, v[86:87]
	ds_bpermute_b32 v82, v241, v82
	ds_bpermute_b32 v83, v241, v83
	ds_bpermute_b32 v84, v241, v84
	ds_bpermute_b32 v85, v241, v85
	s_waitcnt lgkmcnt(0)
	global_store_dwordx4 v[86:87], v[82:85], off offset:256
.LBB0_1255:
	s_or_b64 exec, exec, s[0:1]
	s_nop 0
	v_or_b32_e32 v82, 48, v142
	v_ashrrev_i32_e32 v83, 31, v82
	v_lshlrev_b64 v[84:85], 6, v[82:83]
	v_lshl_add_u64 v[96:97], s[2:3], 0, v[84:85]
	v_mov_b32_e32 v84, v245
	v_mov_b32_e32 v85, v84
	s_and_saveexec_b64 s[0:1], vcc
	s_cbranch_execz .LBB0_1257
	v_mov_b32_e32 v86, v84
	v_mov_b32_e32 v87, v84
	v_pk_mul_f32 v[78:79], v[78:79], v[84:85]
	v_pk_mul_f32 v[74:75], v[74:75], v[84:85]
	v_pk_mul_f32 v[80:81], v[80:81], v[86:87]
	v_max_f32_e32 v78, 0, v78
	v_max_f32_e32 v74, 0, v74
	v_max_f32_e32 v79, 0, v79
	v_max_f32_e32 v75, 0, v75
	v_pk_mul_f32 v[76:77], v[76:77], v[86:87]
	v_pk_mul_f32 v[78:79], v[78:79], v[78:79]
	v_pk_mul_f32 v[86:87], v[74:75], v[74:75]
	v_max_f32_e32 v74, 0, v80
	v_max_f32_e32 v75, 0, v81
	v_max_f32_e32 v76, 0, v76
	v_max_f32_e32 v77, 0, v77
	v_pk_mul_f32 v[80:81], v[74:75], v[74:75]
	v_cvt_pk_bf16_f32 v74, v78, v79
	v_lshlrev_b64 v[78:79], 13, v[82:83]
	v_pk_mul_f32 v[88:89], v[76:77], v[76:77]
	v_lshl_add_u64 v[78:79], s[10:11], 0, v[78:79]
	v_ashrrev_i32_e32 v141, 31, v140
	v_cvt_pk_bf16_f32 v75, v80, v81
	v_cvt_pk_bf16_f32 v76, v86, v87
	v_cvt_pk_bf16_f32 v77, v88, v89
	v_lshl_add_u64 v[78:79], v[140:141], 1, v[78:79]
	ds_bpermute_b32 v74, v241, v74
	ds_bpermute_b32 v75, v241, v75
	ds_bpermute_b32 v76, v241, v76
	ds_bpermute_b32 v77, v241, v77
	s_waitcnt lgkmcnt(0)
	global_store_dwordx4 v[78:79], v[74:77], off
.LBB0_1257:
	s_or_b64 exec, exec, s[0:1]
	s_and_saveexec_b64 s[0:1], s[8:9]
	s_cbranch_execz .LBB0_1259
	v_mov_b32_e32 v74, v84
	v_mov_b32_e32 v75, v84
	v_pk_mul_f32 v[70:71], v[70:71], v[84:85]
	v_pk_mul_f32 v[66:67], v[66:67], v[84:85]
	v_pk_mul_f32 v[72:73], v[72:73], v[74:75]
	v_max_f32_e32 v70, 0, v70
	v_max_f32_e32 v66, 0, v66
	v_max_f32_e32 v71, 0, v71
	v_max_f32_e32 v67, 0, v67
	v_pk_mul_f32 v[68:69], v[68:69], v[74:75]
	v_pk_mul_f32 v[70:71], v[70:71], v[70:71]
	v_pk_mul_f32 v[74:75], v[66:67], v[66:67]
	v_max_f32_e32 v66, 0, v72
	v_max_f32_e32 v67, 0, v73
	v_max_f32_e32 v68, 0, v68
	v_max_f32_e32 v69, 0, v69
	v_pk_mul_f32 v[72:73], v[66:67], v[66:67]
	v_cvt_pk_bf16_f32 v66, v70, v71
	v_lshlrev_b64 v[70:71], 13, v[82:83]
	v_pk_mul_f32 v[76:77], v[68:69], v[68:69]
	v_lshl_add_u64 v[70:71], s[10:11], 0, v[70:71]
	v_ashrrev_i32_e32 v141, 31, v140
	v_cvt_pk_bf16_f32 v67, v72, v73
	v_cvt_pk_bf16_f32 v68, v74, v75
	v_cvt_pk_bf16_f32 v69, v76, v77
	v_lshl_add_u64 v[70:71], v[140:141], 1, v[70:71]
	ds_bpermute_b32 v66, v241, v66
	ds_bpermute_b32 v67, v241, v67
	ds_bpermute_b32 v68, v241, v68
	ds_bpermute_b32 v69, v241, v69
	s_waitcnt lgkmcnt(0)
	global_store_dwordx4 v[70:71], v[66:69], off offset:256
.LBB0_1259:
	s_or_b64 exec, exec, s[0:1]
	s_nop 0
	v_add_u32_e32 v66, 0x80, v142
	v_ashrrev_i32_e32 v67, 31, v66
	v_lshlrev_b64 v[68:69], 6, v[66:67]
	v_lshl_add_u64 v[80:81], s[2:3], 0, v[68:69]
	v_mov_b32_e32 v68, v246
	v_mov_b32_e32 v69, v68
	s_and_saveexec_b64 s[0:1], vcc
	s_cbranch_execz .LBB0_1261
	v_mov_b32_e32 v70, v68
	v_mov_b32_e32 v71, v68
	v_pk_mul_f32 v[62:63], v[62:63], v[68:69]
	v_pk_mul_f32 v[58:59], v[58:59], v[68:69]
	v_pk_mul_f32 v[64:65], v[64:65], v[70:71]
	v_max_f32_e32 v62, 0, v62
	v_max_f32_e32 v58, 0, v58
	v_max_f32_e32 v63, 0, v63
	v_max_f32_e32 v59, 0, v59
	v_pk_mul_f32 v[60:61], v[60:61], v[70:71]
	v_pk_mul_f32 v[62:63], v[62:63], v[62:63]
	v_pk_mul_f32 v[70:71], v[58:59], v[58:59]
	v_max_f32_e32 v58, 0, v64
	v_max_f32_e32 v59, 0, v65
	v_max_f32_e32 v60, 0, v60
	v_max_f32_e32 v61, 0, v61
	v_pk_mul_f32 v[64:65], v[58:59], v[58:59]
	v_cvt_pk_bf16_f32 v58, v62, v63
	v_lshlrev_b64 v[62:63], 13, v[66:67]
	v_pk_mul_f32 v[72:73], v[60:61], v[60:61]
	v_lshl_add_u64 v[62:63], s[10:11], 0, v[62:63]
	v_ashrrev_i32_e32 v141, 31, v140
	v_cvt_pk_bf16_f32 v59, v64, v65
	v_cvt_pk_bf16_f32 v60, v70, v71
	v_cvt_pk_bf16_f32 v61, v72, v73
	v_lshl_add_u64 v[62:63], v[140:141], 1, v[62:63]
	ds_bpermute_b32 v58, v241, v58
	ds_bpermute_b32 v59, v241, v59
	ds_bpermute_b32 v60, v241, v60
	ds_bpermute_b32 v61, v241, v61
	s_waitcnt lgkmcnt(0)
	global_store_dwordx4 v[62:63], v[58:61], off
.LBB0_1261:
	s_or_b64 exec, exec, s[0:1]
	s_and_saveexec_b64 s[0:1], s[8:9]
	s_cbranch_execz .LBB0_1263
	v_mov_b32_e32 v58, v68
	v_mov_b32_e32 v59, v68
	v_pk_mul_f32 v[54:55], v[54:55], v[68:69]
	v_pk_mul_f32 v[50:51], v[50:51], v[68:69]
	v_pk_mul_f32 v[56:57], v[56:57], v[58:59]
	v_max_f32_e32 v54, 0, v54
	v_max_f32_e32 v50, 0, v50
	v_max_f32_e32 v55, 0, v55
	v_max_f32_e32 v51, 0, v51
	v_pk_mul_f32 v[52:53], v[52:53], v[58:59]
	v_pk_mul_f32 v[54:55], v[54:55], v[54:55]
	v_pk_mul_f32 v[58:59], v[50:51], v[50:51]
	v_max_f32_e32 v50, 0, v56
	v_max_f32_e32 v51, 0, v57
	v_max_f32_e32 v52, 0, v52
	v_max_f32_e32 v53, 0, v53
	v_pk_mul_f32 v[56:57], v[50:51], v[50:51]
	v_cvt_pk_bf16_f32 v50, v54, v55
	v_lshlrev_b64 v[54:55], 13, v[66:67]
	v_pk_mul_f32 v[60:61], v[52:53], v[52:53]
	v_lshl_add_u64 v[54:55], s[10:11], 0, v[54:55]
	v_ashrrev_i32_e32 v141, 31, v140
	v_cvt_pk_bf16_f32 v51, v56, v57
	v_cvt_pk_bf16_f32 v52, v58, v59
	v_cvt_pk_bf16_f32 v53, v60, v61
	v_lshl_add_u64 v[54:55], v[140:141], 1, v[54:55]
	ds_bpermute_b32 v50, v241, v50
	ds_bpermute_b32 v51, v241, v51
	ds_bpermute_b32 v52, v241, v52
	ds_bpermute_b32 v53, v241, v53
	s_waitcnt lgkmcnt(0)
	global_store_dwordx4 v[54:55], v[50:53], off offset:256
.LBB0_1263:
	s_or_b64 exec, exec, s[0:1]
	s_nop 0
	v_add_u32_e32 v50, 0x90, v142
	v_ashrrev_i32_e32 v51, 31, v50
	v_lshlrev_b64 v[52:53], 6, v[50:51]
	v_lshl_add_u64 v[64:65], s[2:3], 0, v[52:53]
	v_mov_b32_e32 v52, v247
	v_mov_b32_e32 v53, v52
	s_and_saveexec_b64 s[0:1], vcc
	s_cbranch_execz .LBB0_1265
	v_mov_b32_e32 v54, v52
	v_mov_b32_e32 v55, v52
	v_pk_mul_f32 v[46:47], v[46:47], v[52:53]
	v_pk_mul_f32 v[42:43], v[42:43], v[52:53]
	v_pk_mul_f32 v[48:49], v[48:49], v[54:55]
	v_max_f32_e32 v46, 0, v46
	v_max_f32_e32 v42, 0, v42
	v_max_f32_e32 v47, 0, v47
	v_max_f32_e32 v43, 0, v43
	v_pk_mul_f32 v[44:45], v[44:45], v[54:55]
	v_pk_mul_f32 v[46:47], v[46:47], v[46:47]
	v_pk_mul_f32 v[54:55], v[42:43], v[42:43]
	v_max_f32_e32 v42, 0, v48
	v_max_f32_e32 v43, 0, v49
	v_max_f32_e32 v44, 0, v44
	v_max_f32_e32 v45, 0, v45
	v_pk_mul_f32 v[48:49], v[42:43], v[42:43]
	v_cvt_pk_bf16_f32 v42, v46, v47
	v_lshlrev_b64 v[46:47], 13, v[50:51]
	v_pk_mul_f32 v[56:57], v[44:45], v[44:45]
	v_lshl_add_u64 v[46:47], s[10:11], 0, v[46:47]
	v_ashrrev_i32_e32 v141, 31, v140
	v_cvt_pk_bf16_f32 v43, v48, v49
	v_cvt_pk_bf16_f32 v44, v54, v55
	v_cvt_pk_bf16_f32 v45, v56, v57
	v_lshl_add_u64 v[46:47], v[140:141], 1, v[46:47]
	ds_bpermute_b32 v42, v241, v42
	ds_bpermute_b32 v43, v241, v43
	ds_bpermute_b32 v44, v241, v44
	ds_bpermute_b32 v45, v241, v45
	s_waitcnt lgkmcnt(0)
	global_store_dwordx4 v[46:47], v[42:45], off
.LBB0_1265:
	s_or_b64 exec, exec, s[0:1]
	s_and_saveexec_b64 s[0:1], s[8:9]
	s_cbranch_execz .LBB0_1267
	v_mov_b32_e32 v42, v52
	v_mov_b32_e32 v43, v52
	v_pk_mul_f32 v[38:39], v[38:39], v[52:53]
	v_pk_mul_f32 v[34:35], v[34:35], v[52:53]
	v_pk_mul_f32 v[40:41], v[40:41], v[42:43]
	v_max_f32_e32 v38, 0, v38
	v_max_f32_e32 v34, 0, v34
	v_max_f32_e32 v39, 0, v39
	v_max_f32_e32 v35, 0, v35
	v_pk_mul_f32 v[36:37], v[36:37], v[42:43]
	v_pk_mul_f32 v[38:39], v[38:39], v[38:39]
	v_pk_mul_f32 v[42:43], v[34:35], v[34:35]
	v_max_f32_e32 v34, 0, v40
	v_max_f32_e32 v35, 0, v41
	v_max_f32_e32 v36, 0, v36
	v_max_f32_e32 v37, 0, v37
	v_pk_mul_f32 v[40:41], v[34:35], v[34:35]
	v_cvt_pk_bf16_f32 v34, v38, v39
	v_lshlrev_b64 v[38:39], 13, v[50:51]
	v_pk_mul_f32 v[44:45], v[36:37], v[36:37]
	v_lshl_add_u64 v[38:39], s[10:11], 0, v[38:39]
	v_ashrrev_i32_e32 v141, 31, v140
	v_cvt_pk_bf16_f32 v35, v40, v41
	v_cvt_pk_bf16_f32 v36, v42, v43
	v_cvt_pk_bf16_f32 v37, v44, v45
	v_lshl_add_u64 v[38:39], v[140:141], 1, v[38:39]
	ds_bpermute_b32 v34, v241, v34
	ds_bpermute_b32 v35, v241, v35
	ds_bpermute_b32 v36, v241, v36
	ds_bpermute_b32 v37, v241, v37
	s_waitcnt lgkmcnt(0)
	global_store_dwordx4 v[38:39], v[34:37], off offset:256
.LBB0_1267:
	s_or_b64 exec, exec, s[0:1]
	s_nop 0
	v_add_u32_e32 v34, 0xa0, v142
	v_ashrrev_i32_e32 v35, 31, v34
	v_lshlrev_b64 v[36:37], 6, v[34:35]
	v_lshl_add_u64 v[48:49], s[2:3], 0, v[36:37]
	v_mov_b32_e32 v36, v248
	v_mov_b32_e32 v37, v36
	s_and_saveexec_b64 s[0:1], vcc
	s_cbranch_execz .LBB0_1269
	v_mov_b32_e32 v38, v36
	v_mov_b32_e32 v39, v36
	v_pk_mul_f32 v[30:31], v[30:31], v[36:37]
	v_pk_mul_f32 v[26:27], v[26:27], v[36:37]
	v_pk_mul_f32 v[32:33], v[32:33], v[38:39]
	v_max_f32_e32 v30, 0, v30
	v_max_f32_e32 v26, 0, v26
	v_max_f32_e32 v31, 0, v31
	v_max_f32_e32 v27, 0, v27
	v_pk_mul_f32 v[28:29], v[28:29], v[38:39]
	v_pk_mul_f32 v[30:31], v[30:31], v[30:31]
	v_pk_mul_f32 v[38:39], v[26:27], v[26:27]
	v_max_f32_e32 v26, 0, v32
	v_max_f32_e32 v27, 0, v33
	v_max_f32_e32 v28, 0, v28
	v_max_f32_e32 v29, 0, v29
	v_pk_mul_f32 v[32:33], v[26:27], v[26:27]
	v_cvt_pk_bf16_f32 v26, v30, v31
	v_lshlrev_b64 v[30:31], 13, v[34:35]
	v_pk_mul_f32 v[40:41], v[28:29], v[28:29]
	v_lshl_add_u64 v[30:31], s[10:11], 0, v[30:31]
	v_ashrrev_i32_e32 v141, 31, v140
	v_cvt_pk_bf16_f32 v27, v32, v33
	v_cvt_pk_bf16_f32 v28, v38, v39
	v_cvt_pk_bf16_f32 v29, v40, v41
	v_lshl_add_u64 v[30:31], v[140:141], 1, v[30:31]
	ds_bpermute_b32 v26, v241, v26
	ds_bpermute_b32 v27, v241, v27
	ds_bpermute_b32 v28, v241, v28
	ds_bpermute_b32 v29, v241, v29
	s_waitcnt lgkmcnt(0)
	global_store_dwordx4 v[30:31], v[26:29], off
.LBB0_1269:
	s_or_b64 exec, exec, s[0:1]
	s_and_saveexec_b64 s[0:1], s[8:9]
	s_cbranch_execz .LBB0_1271
	v_mov_b32_e32 v26, v36
	v_mov_b32_e32 v27, v36
	v_pk_mul_f32 v[22:23], v[22:23], v[36:37]
	v_pk_mul_f32 v[18:19], v[18:19], v[36:37]
	v_pk_mul_f32 v[24:25], v[24:25], v[26:27]
	v_max_f32_e32 v22, 0, v22
	v_max_f32_e32 v18, 0, v18
	v_max_f32_e32 v23, 0, v23
	v_max_f32_e32 v19, 0, v19
	v_pk_mul_f32 v[20:21], v[20:21], v[26:27]
	v_pk_mul_f32 v[22:23], v[22:23], v[22:23]
	v_pk_mul_f32 v[26:27], v[18:19], v[18:19]
	v_max_f32_e32 v18, 0, v24
	v_max_f32_e32 v19, 0, v25
	v_max_f32_e32 v20, 0, v20
	v_max_f32_e32 v21, 0, v21
	v_pk_mul_f32 v[24:25], v[18:19], v[18:19]
	v_cvt_pk_bf16_f32 v18, v22, v23
	v_lshlrev_b64 v[22:23], 13, v[34:35]
	v_pk_mul_f32 v[28:29], v[20:21], v[20:21]
	v_lshl_add_u64 v[22:23], s[10:11], 0, v[22:23]
	v_ashrrev_i32_e32 v141, 31, v140
	v_cvt_pk_bf16_f32 v19, v24, v25
	v_cvt_pk_bf16_f32 v20, v26, v27
	v_cvt_pk_bf16_f32 v21, v28, v29
	v_lshl_add_u64 v[22:23], v[140:141], 1, v[22:23]
	ds_bpermute_b32 v18, v241, v18
	ds_bpermute_b32 v19, v241, v19
	ds_bpermute_b32 v20, v241, v20
	ds_bpermute_b32 v21, v241, v21
	s_waitcnt lgkmcnt(0)
	global_store_dwordx4 v[22:23], v[18:21], off offset:256
.LBB0_1271:
	s_or_b64 exec, exec, s[0:1]
	s_nop 0
	v_add_u32_e32 v18, 0xb0, v142
	v_ashrrev_i32_e32 v19, 31, v18
	v_lshlrev_b64 v[20:21], 6, v[18:19]
	v_lshl_add_u64 v[32:33], s[2:3], 0, v[20:21]
	v_mov_b32_e32 v20, v249
	v_mov_b32_e32 v21, v20
	s_and_saveexec_b64 s[0:1], vcc
	s_cbranch_execz .LBB0_1273
	v_mov_b32_e32 v22, v20
	v_mov_b32_e32 v23, v20
	v_pk_mul_f32 v[14:15], v[14:15], v[20:21]
	v_pk_mul_f32 v[10:11], v[10:11], v[20:21]
	v_pk_mul_f32 v[16:17], v[16:17], v[22:23]
	v_max_f32_e32 v14, 0, v14
	v_max_f32_e32 v10, 0, v10
	v_max_f32_e32 v15, 0, v15
	v_max_f32_e32 v11, 0, v11
	v_pk_mul_f32 v[12:13], v[12:13], v[22:23]
	v_pk_mul_f32 v[14:15], v[14:15], v[14:15]
	v_pk_mul_f32 v[22:23], v[10:11], v[10:11]
	v_max_f32_e32 v10, 0, v16
	v_max_f32_e32 v11, 0, v17
	v_max_f32_e32 v12, 0, v12
	v_max_f32_e32 v13, 0, v13
	v_pk_mul_f32 v[16:17], v[10:11], v[10:11]
	v_cvt_pk_bf16_f32 v10, v14, v15
	v_lshlrev_b64 v[14:15], 13, v[18:19]
	v_pk_mul_f32 v[24:25], v[12:13], v[12:13]
	v_lshl_add_u64 v[14:15], s[10:11], 0, v[14:15]
	v_ashrrev_i32_e32 v141, 31, v140
	v_cvt_pk_bf16_f32 v11, v16, v17
	v_cvt_pk_bf16_f32 v12, v22, v23
	v_cvt_pk_bf16_f32 v13, v24, v25
	v_lshl_add_u64 v[14:15], v[140:141], 1, v[14:15]
	ds_bpermute_b32 v10, v241, v10
	ds_bpermute_b32 v11, v241, v11
	ds_bpermute_b32 v12, v241, v12
	ds_bpermute_b32 v13, v241, v13
	s_waitcnt lgkmcnt(0)
	global_store_dwordx4 v[14:15], v[10:13], off
.LBB0_1273:
	s_or_b64 exec, exec, s[0:1]
	s_and_saveexec_b64 s[0:1], s[8:9]
	s_cbranch_execz .LBB0_1275
	v_mov_b32_e32 v10, v20
	v_mov_b32_e32 v11, v20
	v_pk_mul_f32 v[6:7], v[6:7], v[20:21]
	v_pk_mul_f32 v[2:3], v[2:3], v[20:21]
	v_pk_mul_f32 v[8:9], v[8:9], v[10:11]
	v_max_f32_e32 v6, 0, v6
	v_max_f32_e32 v2, 0, v2
	v_max_f32_e32 v7, 0, v7
	v_max_f32_e32 v3, 0, v3
	v_pk_mul_f32 v[4:5], v[4:5], v[10:11]
	v_pk_mul_f32 v[6:7], v[6:7], v[6:7]
	v_pk_mul_f32 v[10:11], v[2:3], v[2:3]
	v_max_f32_e32 v2, 0, v8
	v_max_f32_e32 v3, 0, v9
	v_max_f32_e32 v4, 0, v4
	v_max_f32_e32 v5, 0, v5
	v_pk_mul_f32 v[8:9], v[2:3], v[2:3]
	v_cvt_pk_bf16_f32 v2, v6, v7
	v_lshlrev_b64 v[6:7], 13, v[18:19]
	v_pk_mul_f32 v[12:13], v[4:5], v[4:5]
	v_lshl_add_u64 v[6:7], s[10:11], 0, v[6:7]
	v_ashrrev_i32_e32 v141, 31, v140
	v_cvt_pk_bf16_f32 v3, v8, v9
	v_cvt_pk_bf16_f32 v4, v10, v11
	v_cvt_pk_bf16_f32 v5, v12, v13
	v_lshl_add_u64 v[6:7], v[140:141], 1, v[6:7]
	ds_bpermute_b32 v2, v241, v2
	ds_bpermute_b32 v3, v241, v3
	ds_bpermute_b32 v4, v241, v4
	ds_bpermute_b32 v5, v241, v5
	s_waitcnt lgkmcnt(0)
	global_store_dwordx4 v[6:7], v[2:5], off offset:256
